# residual GEMM (down/mix): per-unit store drain before the K loop removed (only stores are outstanding there)
# baseline (speedup 1.0000x reference)
;     DI bool next(int i, Unit& u) const { if (i > 0 || c >= 44) return false; u.pm = 128 + c / 22; u.pn = c % 22; u.k0 = 0; u.np = 8; return true; }
; #define PG8_STAGE(bufoff, gbase, voff) do { _Pragma("unroll") for (int _i = 0; _i < 2; ++_i) \
;         __builtin_amdgcn_global_load_lds((const unsigned*)((const char*)(gbase) + (voff)[_i]), (LAS unsigned*)(lds + (bufoff) + ldsw + _i * 8192), 16, 0, 0); } while (0)
; #define PG8_LDA(dst, b, h) do { _Pragma("unroll") for (int m = 0; m < 4; ++m) _Pragma("unroll") for (int k = 0; k < 2; ++k) dst[m][k] = *(const LAS bf16x8*)(lds + PG8_SA(b, h) + aoff + m * 2048 + k * 1024); } while (0)
; #define PG8_LDB(dst, b, h) do { _Pragma("unroll") for (int n = 0; n < 2; ++n) _Pragma("unroll") for (int k = 0; k < 2; ++k) dst[n][k] = *(const LAS bf16x8*)(lds + PG8_SB(b, h) + boff + n * 2048 + k * 1024); } while (0)
; #define PG8_WAIT_V(n) asm volatile("s_waitcnt vmcnt(" #n ")" ::: "memory")
; template <class Epi, class Sched>
; DI void gemm_phase(LAS unsigned char* lds, const Gemm g, const Sched& S, const Epi& E, const int tid) {
;     ...
;     for (;;) {
;         const bool has_next = S.next(ui + 1, nxt);
;         const char* nA = has_next ? (const char*)g.A + (size_t)nxt.pm * tstepA + (size_t)nxt.pn * g.acol * 2 + (size_t)nxt.k0 * 256 : cA; const char* nB = has_next ? (const char*)g.Bt + (size_t)nxt.pn * tstepB + (size_t)nxt.k0 * 256 : cB;
;         const int nt = 2 * cur.np;
;         for (int t = 0; t < nt; t += 2) {
;             const bool last = (t == nt - 2);
;             const char* a1 = cA + (size_t)(t + 1) * kstep;
;             const char* a2 = last ? nA : cA + (size_t)(t + 2) * kstep; const char* b2 = last ? nB : cB + (size_t)(t + 2) * kstep;
;             const char* a3 = a2 + kstep; const char* b3 = b2 + kstep;
;             PG8_LDB(B0, 0, 0); PG8_LDB(B1, 0, 1); PG8_SCHED; PG8_LDA(At, 0, 0); PG8_STAGE(PG8_SA(1, 1), a1 + hstepA, voffA);
;             PG8_WAIT_V(8); PG8_WAIT_L(0); PG8_BAR; PG8_MMA(0, 0, At, B0); PG8_MMA(0, 1, At, B1); PG8_BAR; PG8_SCHED;
;     ...
; #pragma unroll
;         for (int a = 0; a < 2; ++a)
; #pragma unroll
;             for (int b = 0; b < 2; ++b)
; #pragma unroll
;                 for (int m = 0; m < 4; ++m)
; #pragma unroll
;                     for (int n = 0; n < 2; ++n) acc[a][b][m][n] = (f32x4){0.f, 0.f, 0.f, 0.f};
;         cur = nxt; cA = nA; cB = nB; ++ui;
.LBB0_1375:
	s_lshl_b32 s10, s75, 1
	s_add_i32 s11, s10, -2
	s_add_u32 s12, s4, 0x100
	s_addc_u32 s13, s5, 0
	s_add_u32 s0, s6, 0x80
	v_mov_b32_e32 v0, 0
	s_addc_u32 s1, s7, 0
	s_mov_b32 s4, 0
	v_mov_b32_e32 v1, v0
	v_mov_b32_e32 v2, v0
	v_mov_b32_e32 v3, v0
	v_mov_b32_e32 v4, v0
	v_mov_b32_e32 v5, v0
	v_mov_b32_e32 v6, v0
	v_mov_b32_e32 v7, v0
	v_mov_b32_e32 v12, v0
	v_mov_b32_e32 v13, v0
	v_mov_b32_e32 v14, v0
	v_mov_b32_e32 v15, v0
	v_mov_b32_e32 v16, v0
	v_mov_b32_e32 v17, v0
	v_mov_b32_e32 v18, v0
	v_mov_b32_e32 v19, v0
	v_mov_b32_e32 v28, v0
	v_mov_b32_e32 v29, v0
	v_mov_b32_e32 v30, v0
	v_mov_b32_e32 v31, v0
	v_mov_b32_e32 v32, v0
	v_mov_b32_e32 v33, v0
	v_mov_b32_e32 v34, v0
	v_mov_b32_e32 v35, v0
	v_mov_b32_e32 v44, v0
	v_mov_b32_e32 v45, v0
	v_mov_b32_e32 v46, v0
	v_mov_b32_e32 v47, v0
	v_mov_b32_e32 v48, v0
	v_mov_b32_e32 v49, v0
	v_mov_b32_e32 v50, v0
	v_mov_b32_e32 v51, v0
	v_mov_b32_e32 v8, v0
	v_mov_b32_e32 v9, v0
	v_mov_b32_e32 v10, v0
	v_mov_b32_e32 v11, v0
	v_mov_b32_e32 v20, v0
	v_mov_b32_e32 v21, v0
	v_mov_b32_e32 v22, v0
	v_mov_b32_e32 v23, v0
	v_mov_b32_e32 v24, v0
	v_mov_b32_e32 v25, v0
	v_mov_b32_e32 v26, v0
	v_mov_b32_e32 v27, v0
	v_mov_b32_e32 v36, v0
	v_mov_b32_e32 v37, v0
	v_mov_b32_e32 v38, v0
	v_mov_b32_e32 v39, v0
	v_mov_b32_e32 v40, v0
	v_mov_b32_e32 v41, v0
	v_mov_b32_e32 v42, v0
	v_mov_b32_e32 v43, v0
	v_mov_b32_e32 v52, v0
	v_mov_b32_e32 v53, v0
	v_mov_b32_e32 v54, v0
	v_mov_b32_e32 v55, v0
	v_mov_b32_e32 v56, v0
	v_mov_b32_e32 v57, v0
	v_mov_b32_e32 v58, v0
	v_mov_b32_e32 v59, v0
	v_mov_b32_e32 v60, v0
	v_mov_b32_e32 v61, v0
	v_mov_b32_e32 v62, v0
	v_mov_b32_e32 v63, v0
	v_mov_b32_e32 v66, v0
	v_mov_b32_e32 v67, v0
	v_mov_b32_e32 v68, v0
	v_mov_b32_e32 v69, v0
	v_mov_b32_e32 v70, v0
	v_mov_b32_e32 v71, v0
	v_mov_b32_e32 v72, v0
	v_mov_b32_e32 v73, v0
	v_mov_b32_e32 v78, v0
	v_mov_b32_e32 v79, v0
	v_mov_b32_e32 v80, v0
	v_mov_b32_e32 v81, v0
	v_mov_b32_e32 v86, v0
	v_mov_b32_e32 v87, v0
	v_mov_b32_e32 v88, v0
	v_mov_b32_e32 v89, v0
	v_mov_b32_e32 v94, v0
	v_mov_b32_e32 v95, v0
	v_mov_b32_e32 v96, v0
	v_mov_b32_e32 v97, v0
	v_mov_b32_e32 v102, v0
	v_mov_b32_e32 v103, v0
	v_mov_b32_e32 v104, v0
	v_mov_b32_e32 v105, v0
	v_mov_b32_e32 v110, v0
	v_mov_b32_e32 v111, v0
	v_mov_b32_e32 v112, v0
	v_mov_b32_e32 v113, v0
	v_mov_b32_e32 v118, v0
	v_mov_b32_e32 v119, v0
	v_mov_b32_e32 v120, v0
	v_mov_b32_e32 v121, v0
	v_mov_b32_e32 v74, v0
	v_mov_b32_e32 v75, v0
	v_mov_b32_e32 v76, v0
	v_mov_b32_e32 v77, v0
	v_mov_b32_e32 v82, v0
	v_mov_b32_e32 v83, v0
	v_mov_b32_e32 v84, v0
	v_mov_b32_e32 v85, v0
	v_mov_b32_e32 v90, v0
	v_mov_b32_e32 v91, v0
	v_mov_b32_e32 v92, v0
	v_mov_b32_e32 v93, v0
	v_mov_b32_e32 v98, v0
	v_mov_b32_e32 v99, v0
	v_mov_b32_e32 v100, v0
	v_mov_b32_e32 v101, v0
	v_mov_b32_e32 v106, v0
	v_mov_b32_e32 v107, v0
	v_mov_b32_e32 v108, v0
	v_mov_b32_e32 v109, v0
	v_mov_b32_e32 v114, v0
	v_mov_b32_e32 v115, v0
	v_mov_b32_e32 v116, v0
	v_mov_b32_e32 v117, v0
	v_mov_b32_e32 v122, v0
	v_mov_b32_e32 v123, v0
	v_mov_b32_e32 v124, v0
	v_mov_b32_e32 v125, v0
	v_mov_b32_e32 v126, v0
	v_mov_b32_e32 v127, v0
	v_mov_b32_e32 v128, v0
	v_mov_b32_e32 v129, v0
.LBB0_1376:
	s_add_i32 s6, s4, 2
	s_add_u32 s7, s0, 0x80
	s_addc_u32 s5, s1, 0
	s_add_i32 s27, 0, 0x10000
	s_cmp_eq_u32 s11, s4
	s_cselect_b32 s5, s35, s5
	s_cselect_b32 s4, s34, s7
	s_cselect_b32 s77, s57, s13
	s_cselect_b32 s76, s56, s12
	s_add_i32 s7, 0, 0x14000
	v_add_u32_e32 v142, s27, v195
	v_add_u32_e32 v158, s7, v195
	ds_read_b128 v[130:133], v142
	ds_read_b128 v[134:137], v142 offset:1024
	ds_read_b128 v[138:141], v142 offset:2048
	ds_read_b128 v[142:145], v142 offset:3072
	ds_read_b128 v[146:149], v158
	ds_read_b128 v[150:153], v158 offset:1024
	ds_read_b128 v[154:157], v158 offset:2048
	ds_read_b128 v[158:161], v158 offset:3072
	v_lshl_add_u64 v[192:193], s[0:1], 0, v[186:187]
	s_add_i32 m0, s60, 0xc000
	ds_read_b128 v[162:165], v198
	ds_read_b128 v[166:169], v198 offset:1024
	ds_read_b128 v[170:173], v198 offset:2048
	ds_read_b128 v[174:177], v198 offset:3072
	ds_read_b128 v[188:191], v198 offset:4096
	ds_read_b128 v[200:203], v198 offset:5120
	ds_read_b128 v[204:207], v198 offset:6144
	ds_read_b128 v[208:211], v198 offset:7168
	global_load_lds_dwordx4 v[192:193], off
	v_lshl_add_u64 v[192:193], s[0:1], 0, v[184:185]
	s_add_i32 m0, s60, 0xe000
	s_nop 0
	global_load_lds_dwordx4 v[192:193], off
	s_waitcnt vmcnt(8)
	s_waitcnt lgkmcnt(0)
	s_barrier
	s_setprio 1
	s_waitcnt lgkmcnt(0)
	v_mfma_f32_16x16x32_bf16 v[126:129], v[130:133], v[162:165], v[126:129]
	v_mfma_f32_16x16x32_bf16 v[122:125], v[138:141], v[162:165], v[122:125]
	v_mfma_f32_16x16x32_bf16 v[114:117], v[130:133], v[170:173], v[114:117]
	v_mfma_f32_16x16x32_bf16 v[106:109], v[138:141], v[170:173], v[106:109]
	v_mfma_f32_16x16x32_bf16 v[98:101], v[130:133], v[188:191], v[98:101]
	v_mfma_f32_16x16x32_bf16 v[90:93], v[138:141], v[188:191], v[90:93]
	v_mfma_f32_16x16x32_bf16 v[82:85], v[130:133], v[204:207], v[82:85]
	v_mfma_f32_16x16x32_bf16 v[74:77], v[138:141], v[204:207], v[74:77]
	v_mfma_f32_16x16x32_bf16 v[126:129], v[134:137], v[166:169], v[126:129]
	v_mfma_f32_16x16x32_bf16 v[122:125], v[142:145], v[166:169], v[122:125]
	v_mfma_f32_16x16x32_bf16 v[114:117], v[134:137], v[174:177], v[114:117]
	v_mfma_f32_16x16x32_bf16 v[106:109], v[142:145], v[174:177], v[106:109]
	v_mfma_f32_16x16x32_bf16 v[98:101], v[134:137], v[200:203], v[98:101]
	v_mfma_f32_16x16x32_bf16 v[90:93], v[142:145], v[200:203], v[90:93]
	v_mfma_f32_16x16x32_bf16 v[82:85], v[134:137], v[208:211], v[82:85]
	v_mfma_f32_16x16x32_bf16 v[74:77], v[142:145], v[208:211], v[74:77]
	s_setprio 0
	s_setprio 1
	v_mfma_f32_16x16x32_bf16 v[118:121], v[146:149], v[162:165], v[118:121]
	v_mfma_f32_16x16x32_bf16 v[110:113], v[154:157], v[162:165], v[110:113]
	v_mfma_f32_16x16x32_bf16 v[102:105], v[146:149], v[170:173], v[102:105]
	v_mfma_f32_16x16x32_bf16 v[94:97], v[154:157], v[170:173], v[94:97]
	v_mfma_f32_16x16x32_bf16 v[86:89], v[146:149], v[188:191], v[86:89]
	v_mfma_f32_16x16x32_bf16 v[78:81], v[154:157], v[188:191], v[78:81]
	v_mfma_f32_16x16x32_bf16 v[70:73], v[146:149], v[204:207], v[70:73]
	v_mfma_f32_16x16x32_bf16 v[66:69], v[154:157], v[204:207], v[66:69]
	v_mfma_f32_16x16x32_bf16 v[118:121], v[150:153], v[166:169], v[118:121]
	v_mfma_f32_16x16x32_bf16 v[110:113], v[158:161], v[166:169], v[110:113]
	v_mfma_f32_16x16x32_bf16 v[102:105], v[150:153], v[174:177], v[102:105]
	v_mfma_f32_16x16x32_bf16 v[94:97], v[158:161], v[174:177], v[94:97]
	v_mfma_f32_16x16x32_bf16 v[86:89], v[150:153], v[200:203], v[86:89]
	v_mfma_f32_16x16x32_bf16 v[78:81], v[158:161], v[200:203], v[78:81]
	v_mfma_f32_16x16x32_bf16 v[70:73], v[150:153], v[208:211], v[70:73]
	v_mfma_f32_16x16x32_bf16 v[66:69], v[158:161], v[208:211], v[66:69]
	s_setprio 0
	s_barrier
; #define PG8_STAGE(bufoff, gbase, voff) do { _Pragma("unroll") for (int _i = 0; _i < 2; ++_i) \
;         __builtin_amdgcn_global_load_lds((const unsigned*)((const char*)(gbase) + (voff)[_i]), (LAS unsigned*)(lds + (bufoff) + ldsw + _i * 8192), 16, 0, 0); } while (0)
; #define PG8_LDA(dst, b, h) do { _Pragma("unroll") for (int m = 0; m < 4; ++m) _Pragma("unroll") for (int k = 0; k < 2; ++k) dst[m][k] = *(const LAS bf16x8*)(lds + PG8_SA(b, h) + aoff + m * 2048 + k * 1024); } while (0)
; #define PG8_LDB(dst, b, h) do { _Pragma("unroll") for (int n = 0; n < 2; ++n) _Pragma("unroll") for (int k = 0; k < 2; ++k) dst[n][k] = *(const LAS bf16x8*)(lds + PG8_SB(b, h) + boff + n * 2048 + k * 1024); } while (0)
; #define PG8_MMA(ai, bj, At, Bt) do { __builtin_amdgcn_s_setprio(1); _Pragma("unroll") for (int m = 0; m < 4; ++m) _Pragma("unroll") for (int n = 0; n < 2; ++n) _Pragma("unroll") for (int k = 0; k < 2; ++k) \
;         acc[ai][bj][m][n] = __builtin_amdgcn_mfma_f32_16x16x32_bf16(Bt[n][k], At[m][k], acc[ai][bj][m][n], 0, 0, 0); __builtin_amdgcn_s_setprio(0); } while (0)
; #define PG8_WAIT_V(n) asm volatile("s_waitcnt vmcnt(" #n ")" ::: "memory")
; #define PG8_WAIT_L(n) asm volatile("s_waitcnt lgkmcnt(" #n ")" ::: "memory")
; #define PG8_BAR __builtin_amdgcn_s_barrier()
; #define PG8_SCHED __builtin_amdgcn_sched_barrier(0)
; template <class Epi, class Sched>
; DI void gemm_phase(LAS unsigned char* lds, const Gemm g, const Sched& S, const Epi& E, const int tid) {
;     ...
;             PG8_LDA(At, 0, 1); PG8_STAGE(PG8_SB(0, 0), b2, voffB); PG8_STAGE(PG8_SB(0, 1), b2 + hstepB, voffB); PG8_STAGE(PG8_SA(0, 0), a2, voffA);
;             PG8_WAIT_V(8); PG8_WAIT_L(0); PG8_BAR; PG8_MMA(1, 0, At, B0); PG8_MMA(1, 1, At, B1); PG8_BAR; PG8_SCHED;
;             PG8_LDB(B0, 1, 0); PG8_LDB(B1, 1, 1); PG8_SCHED; PG8_LDA(At, 1, 0); PG8_STAGE(PG8_SA(0, 1), a2 + hstepA, voffA);
;             PG8_WAIT_V(8); PG8_WAIT_L(0); PG8_BAR; PG8_MMA(0, 0, At, B0); PG8_MMA(0, 1, At, B1); PG8_BAR; PG8_SCHED;
	s_add_i32 s27, s27, s59
	v_lshl_add_u64 v[192:193], s[76:77], 0, v[64:65]
	s_mov_b32 m0, s27
	ds_read_b128 v[162:165], v198 offset:16384
	ds_read_b128 v[166:169], v198 offset:17408
	ds_read_b128 v[170:173], v198 offset:18432
	ds_read_b128 v[174:177], v198 offset:19456
	ds_read_b128 v[188:191], v198 offset:20480
	ds_read_b128 v[200:203], v198 offset:21504
	ds_read_b128 v[204:207], v198 offset:22528
	ds_read_b128 v[208:211], v198 offset:23552
	global_load_lds_dwordx4 v[192:193], off
	s_add_i32 m0, s27, 0x2000
	v_lshl_add_u64 v[212:213], s[76:77], 0, v[182:183]
	s_add_u32 s76, s76, s18
	s_addc_u32 s77, s77, 0
	s_add_i32 s7, s7, s59
	global_load_lds_dwordx4 v[212:213], off
	v_lshl_add_u64 v[214:215], s[76:77], 0, v[64:65]
	s_mov_b32 m0, s7
	v_lshl_add_u64 v[218:219], s[76:77], 0, v[182:183]
	global_load_lds_dwordx4 v[214:215], off
	s_add_i32 m0, s7, 0x2000
	v_lshl_add_u64 v[220:221], s[4:5], 0, v[178:179]
	global_load_lds_dwordx4 v[218:219], off
	s_mov_b32 m0, s60
	v_lshl_add_u64 v[224:225], s[4:5], 0, v[180:181]
	global_load_lds_dwordx4 v[220:221], off
	s_mov_b32 m0, s61
	s_nop 0
	global_load_lds_dwordx4 v[224:225], off
	s_waitcnt vmcnt(8)
	s_waitcnt lgkmcnt(0)
	s_barrier
	s_setprio 1
	s_waitcnt lgkmcnt(0)
	v_mfma_f32_16x16x32_bf16 v[60:63], v[130:133], v[162:165], v[60:63]
	v_mfma_f32_16x16x32_bf16 v[56:59], v[138:141], v[162:165], v[56:59]
	v_mfma_f32_16x16x32_bf16 v[52:55], v[130:133], v[170:173], v[52:55]
	v_mfma_f32_16x16x32_bf16 v[40:43], v[138:141], v[170:173], v[40:43]
	v_mfma_f32_16x16x32_bf16 v[36:39], v[130:133], v[188:191], v[36:39]
	v_mfma_f32_16x16x32_bf16 v[24:27], v[138:141], v[188:191], v[24:27]
	v_mfma_f32_16x16x32_bf16 v[20:23], v[130:133], v[204:207], v[20:23]
	v_mfma_f32_16x16x32_bf16 v[8:11], v[138:141], v[204:207], v[8:11]
	v_mfma_f32_16x16x32_bf16 v[60:63], v[134:137], v[166:169], v[60:63]
	v_mfma_f32_16x16x32_bf16 v[56:59], v[142:145], v[166:169], v[56:59]
	v_mfma_f32_16x16x32_bf16 v[52:55], v[134:137], v[174:177], v[52:55]
	v_mfma_f32_16x16x32_bf16 v[40:43], v[142:145], v[174:177], v[40:43]
	v_mfma_f32_16x16x32_bf16 v[36:39], v[134:137], v[200:203], v[36:39]
	v_mfma_f32_16x16x32_bf16 v[24:27], v[142:145], v[200:203], v[24:27]
	v_mfma_f32_16x16x32_bf16 v[20:23], v[134:137], v[208:211], v[20:23]
	v_mfma_f32_16x16x32_bf16 v[8:11], v[142:145], v[208:211], v[8:11]
	s_setprio 0
	s_setprio 1
	v_mfma_f32_16x16x32_bf16 v[48:51], v[146:149], v[162:165], v[48:51]
	v_mfma_f32_16x16x32_bf16 v[44:47], v[154:157], v[162:165], v[44:47]
	v_mfma_f32_16x16x32_bf16 v[32:35], v[146:149], v[170:173], v[32:35]
	v_mfma_f32_16x16x32_bf16 v[28:31], v[154:157], v[170:173], v[28:31]
	v_mfma_f32_16x16x32_bf16 v[16:19], v[146:149], v[188:191], v[16:19]
	v_mfma_f32_16x16x32_bf16 v[12:15], v[154:157], v[188:191], v[12:15]
	v_mfma_f32_16x16x32_bf16 v[4:7], v[146:149], v[204:207], v[4:7]
	v_mfma_f32_16x16x32_bf16 v[0:3], v[154:157], v[204:207], v[0:3]
	v_mfma_f32_16x16x32_bf16 v[48:51], v[150:153], v[166:169], v[48:51]
	v_mfma_f32_16x16x32_bf16 v[44:47], v[158:161], v[166:169], v[44:47]
	v_mfma_f32_16x16x32_bf16 v[32:35], v[150:153], v[174:177], v[32:35]
	v_mfma_f32_16x16x32_bf16 v[28:31], v[158:161], v[174:177], v[28:31]
	v_mfma_f32_16x16x32_bf16 v[16:19], v[150:153], v[200:203], v[16:19]
	v_mfma_f32_16x16x32_bf16 v[12:15], v[158:161], v[200:203], v[12:15]
	v_mfma_f32_16x16x32_bf16 v[4:7], v[150:153], v[208:211], v[4:7]
	v_mfma_f32_16x16x32_bf16 v[0:3], v[158:161], v[208:211], v[0:3]
	s_setprio 0
	s_barrier
	s_add_i32 s7, 0, 0x18000
	s_add_i32 s27, 0, 0x1c000
	v_add_u32_e32 v142, s7, v195
	v_add_u32_e32 v158, s27, v195
	ds_read_b128 v[130:133], v142
	ds_read_b128 v[134:137], v142 offset:1024
	ds_read_b128 v[138:141], v142 offset:2048
	ds_read_b128 v[142:145], v142 offset:3072
	ds_read_b128 v[146:149], v158
	ds_read_b128 v[150:153], v158 offset:1024
	ds_read_b128 v[154:157], v158 offset:2048
	ds_read_b128 v[158:161], v158 offset:3072
	s_add_u32 s4, s4, s8
	s_addc_u32 s5, s5, 0
	s_mov_b32 m0, s62
	v_lshl_add_u64 v[226:227], s[4:5], 0, v[178:179]
	ds_read_b128 v[162:165], v198 offset:32768
	ds_read_b128 v[166:169], v198 offset:33792
	ds_read_b128 v[170:173], v198 offset:34816
	ds_read_b128 v[174:177], v198 offset:35840
	ds_read_b128 v[188:191], v198 offset:36864
	ds_read_b128 v[200:203], v198 offset:37888
	ds_read_b128 v[204:207], v198 offset:38912
	ds_read_b128 v[208:211], v198 offset:39936
	global_load_lds_dwordx4 v[226:227], off
	v_lshl_add_u64 v[226:227], s[4:5], 0, v[180:181]
	s_mov_b32 m0, s63
	s_nop 0
	global_load_lds_dwordx4 v[226:227], off
	s_waitcnt vmcnt(8)
	s_waitcnt lgkmcnt(0)
	s_barrier
; #define PG8_STAGE(bufoff, gbase, voff) do { _Pragma("unroll") for (int _i = 0; _i < 2; ++_i) \
;         __builtin_amdgcn_global_load_lds((const unsigned*)((const char*)(gbase) + (voff)[_i]), (LAS unsigned*)(lds + (bufoff) + ldsw + _i * 8192), 16, 0, 0); } while (0)
; #define PG8_LDA(dst, b, h) do { _Pragma("unroll") for (int m = 0; m < 4; ++m) _Pragma("unroll") for (int k = 0; k < 2; ++k) dst[m][k] = *(const LAS bf16x8*)(lds + PG8_SA(b, h) + aoff + m * 2048 + k * 1024); } while (0)
; #define PG8_MMA(ai, bj, At, Bt) do { __builtin_amdgcn_s_setprio(1); _Pragma("unroll") for (int m = 0; m < 4; ++m) _Pragma("unroll") for (int n = 0; n < 2; ++n) _Pragma("unroll") for (int k = 0; k < 2; ++k) \
;         acc[ai][bj][m][n] = __builtin_amdgcn_mfma_f32_16x16x32_bf16(Bt[n][k], At[m][k], acc[ai][bj][m][n], 0, 0, 0); __builtin_amdgcn_s_setprio(0); } while (0)
; #define PG8_WAIT_V(n) asm volatile("s_waitcnt vmcnt(" #n ")" ::: "memory")
; #define PG8_WAIT_L(n) asm volatile("s_waitcnt lgkmcnt(" #n ")" ::: "memory")
; #define PG8_BAR __builtin_amdgcn_s_barrier()
; #define PG8_SCHED __builtin_amdgcn_sched_barrier(0)
; template <class Epi, class Sched>
; DI void gemm_phase(LAS unsigned char* lds, const Gemm g, const Sched& S, const Epi& E, const int tid) {
;     ...
;             PG8_WAIT_V(8); PG8_WAIT_L(0); PG8_BAR; PG8_MMA(0, 0, At, B0); PG8_MMA(0, 1, At, B1); PG8_BAR; PG8_SCHED;
;             PG8_LDA(At, 1, 1); PG8_STAGE(PG8_SB(1, 0), b3, voffB); PG8_STAGE(PG8_SB(1, 1), b3 + hstepB, voffB); PG8_STAGE(PG8_SA(1, 0), a3, voffA);
;             PG8_WAIT_V(8); PG8_WAIT_L(0); PG8_BAR; PG8_MMA(1, 0, At, B0); PG8_MMA(1, 1, At, B1); PG8_BAR; PG8_SCHED;
;         }
;         if (wr == 0) PG8_BAR;
	s_setprio 1
	s_waitcnt lgkmcnt(0)
	v_mfma_f32_16x16x32_bf16 v[126:129], v[130:133], v[162:165], v[126:129]
	v_mfma_f32_16x16x32_bf16 v[122:125], v[138:141], v[162:165], v[122:125]
	v_mfma_f32_16x16x32_bf16 v[114:117], v[130:133], v[170:173], v[114:117]
	v_mfma_f32_16x16x32_bf16 v[106:109], v[138:141], v[170:173], v[106:109]
	v_mfma_f32_16x16x32_bf16 v[98:101], v[130:133], v[188:191], v[98:101]
	v_mfma_f32_16x16x32_bf16 v[90:93], v[138:141], v[188:191], v[90:93]
	v_mfma_f32_16x16x32_bf16 v[82:85], v[130:133], v[204:207], v[82:85]
	v_mfma_f32_16x16x32_bf16 v[74:77], v[138:141], v[204:207], v[74:77]
	v_mfma_f32_16x16x32_bf16 v[126:129], v[134:137], v[166:169], v[126:129]
	v_mfma_f32_16x16x32_bf16 v[122:125], v[142:145], v[166:169], v[122:125]
	v_mfma_f32_16x16x32_bf16 v[114:117], v[134:137], v[174:177], v[114:117]
	v_mfma_f32_16x16x32_bf16 v[106:109], v[142:145], v[174:177], v[106:109]
	v_mfma_f32_16x16x32_bf16 v[98:101], v[134:137], v[200:203], v[98:101]
	v_mfma_f32_16x16x32_bf16 v[90:93], v[142:145], v[200:203], v[90:93]
	v_mfma_f32_16x16x32_bf16 v[82:85], v[134:137], v[208:211], v[82:85]
	v_mfma_f32_16x16x32_bf16 v[74:77], v[142:145], v[208:211], v[74:77]
	s_setprio 0
	s_setprio 1
	v_mfma_f32_16x16x32_bf16 v[118:121], v[146:149], v[162:165], v[118:121]
	v_mfma_f32_16x16x32_bf16 v[110:113], v[154:157], v[162:165], v[110:113]
	v_mfma_f32_16x16x32_bf16 v[102:105], v[146:149], v[170:173], v[102:105]
	v_mfma_f32_16x16x32_bf16 v[94:97], v[154:157], v[170:173], v[94:97]
	v_mfma_f32_16x16x32_bf16 v[86:89], v[146:149], v[188:191], v[86:89]
	v_mfma_f32_16x16x32_bf16 v[78:81], v[154:157], v[188:191], v[78:81]
	v_mfma_f32_16x16x32_bf16 v[70:73], v[146:149], v[204:207], v[70:73]
	v_mfma_f32_16x16x32_bf16 v[66:69], v[154:157], v[204:207], v[66:69]
	v_mfma_f32_16x16x32_bf16 v[118:121], v[150:153], v[166:169], v[118:121]
	v_mfma_f32_16x16x32_bf16 v[110:113], v[158:161], v[166:169], v[110:113]
	v_mfma_f32_16x16x32_bf16 v[102:105], v[150:153], v[174:177], v[102:105]
	v_mfma_f32_16x16x32_bf16 v[94:97], v[158:161], v[174:177], v[94:97]
	v_mfma_f32_16x16x32_bf16 v[86:89], v[150:153], v[200:203], v[86:89]
	v_mfma_f32_16x16x32_bf16 v[78:81], v[158:161], v[200:203], v[78:81]
	v_mfma_f32_16x16x32_bf16 v[70:73], v[150:153], v[208:211], v[70:73]
	v_mfma_f32_16x16x32_bf16 v[66:69], v[158:161], v[208:211], v[66:69]
	s_setprio 0
	s_barrier
	s_add_i32 s4, s7, s59
	v_lshl_add_u64 v[192:193], v[192:193], 0, s[24:25]
	s_mov_b32 m0, s4
	ds_read_b128 v[162:165], v198 offset:49152
	ds_read_b128 v[166:169], v198 offset:50176
	ds_read_b128 v[170:173], v198 offset:51200
	ds_read_b128 v[174:177], v198 offset:52224
	ds_read_b128 v[188:191], v198 offset:53248
	ds_read_b128 v[200:203], v198 offset:54272
	ds_read_b128 v[204:207], v198 offset:55296
	ds_read_b128 v[208:211], v198 offset:56320
	global_load_lds_dwordx4 v[192:193], off
	v_lshl_add_u64 v[192:193], v[212:213], 0, s[24:25]
	s_add_i32 m0, s4, 0x2000
	s_add_i32 s4, s27, s59
	global_load_lds_dwordx4 v[192:193], off
	v_lshl_add_u64 v[192:193], v[214:215], 0, s[24:25]
	s_mov_b32 m0, s4
	s_nop 0
	global_load_lds_dwordx4 v[192:193], off
	v_lshl_add_u64 v[192:193], v[218:219], 0, s[24:25]
	s_add_i32 m0, s4, 0x2000
	s_nop 0
	global_load_lds_dwordx4 v[192:193], off
	v_lshl_add_u64 v[192:193], v[220:221], 0, s[24:25]
	s_mov_b32 m0, s66
	s_nop 0
	global_load_lds_dwordx4 v[192:193], off
	v_lshl_add_u64 v[192:193], v[224:225], 0, s[24:25]
	s_mov_b32 m0, s67
	s_nop 0
	global_load_lds_dwordx4 v[192:193], off
	s_waitcnt vmcnt(8)
	s_waitcnt lgkmcnt(0)
	s_barrier
	s_setprio 1
	s_waitcnt lgkmcnt(0)
	v_mfma_f32_16x16x32_bf16 v[60:63], v[130:133], v[162:165], v[60:63]
	v_mfma_f32_16x16x32_bf16 v[56:59], v[138:141], v[162:165], v[56:59]
	v_mfma_f32_16x16x32_bf16 v[52:55], v[130:133], v[170:173], v[52:55]
	v_mfma_f32_16x16x32_bf16 v[40:43], v[138:141], v[170:173], v[40:43]
	v_mfma_f32_16x16x32_bf16 v[36:39], v[130:133], v[188:191], v[36:39]
	v_mfma_f32_16x16x32_bf16 v[24:27], v[138:141], v[188:191], v[24:27]
	v_mfma_f32_16x16x32_bf16 v[20:23], v[130:133], v[204:207], v[20:23]
	v_mfma_f32_16x16x32_bf16 v[8:11], v[138:141], v[204:207], v[8:11]
	v_mfma_f32_16x16x32_bf16 v[60:63], v[134:137], v[166:169], v[60:63]
	v_mfma_f32_16x16x32_bf16 v[56:59], v[142:145], v[166:169], v[56:59]
	v_mfma_f32_16x16x32_bf16 v[52:55], v[134:137], v[174:177], v[52:55]
	v_mfma_f32_16x16x32_bf16 v[40:43], v[142:145], v[174:177], v[40:43]
	v_mfma_f32_16x16x32_bf16 v[36:39], v[134:137], v[200:203], v[36:39]
	v_mfma_f32_16x16x32_bf16 v[24:27], v[142:145], v[200:203], v[24:27]
	v_mfma_f32_16x16x32_bf16 v[20:23], v[134:137], v[208:211], v[20:23]
	v_mfma_f32_16x16x32_bf16 v[8:11], v[142:145], v[208:211], v[8:11]
	s_setprio 0
	s_setprio 1
	v_mfma_f32_16x16x32_bf16 v[48:51], v[146:149], v[162:165], v[48:51]
	v_mfma_f32_16x16x32_bf16 v[44:47], v[154:157], v[162:165], v[44:47]
	v_mfma_f32_16x16x32_bf16 v[32:35], v[146:149], v[170:173], v[32:35]
	v_mfma_f32_16x16x32_bf16 v[28:31], v[154:157], v[170:173], v[28:31]
	v_mfma_f32_16x16x32_bf16 v[16:19], v[146:149], v[188:191], v[16:19]
	v_mfma_f32_16x16x32_bf16 v[12:15], v[154:157], v[188:191], v[12:15]
	v_mfma_f32_16x16x32_bf16 v[4:7], v[146:149], v[204:207], v[4:7]
	v_mfma_f32_16x16x32_bf16 v[0:3], v[154:157], v[204:207], v[0:3]
	v_mfma_f32_16x16x32_bf16 v[48:51], v[150:153], v[166:169], v[48:51]
	v_mfma_f32_16x16x32_bf16 v[44:47], v[158:161], v[166:169], v[44:47]
	v_mfma_f32_16x16x32_bf16 v[32:35], v[150:153], v[174:177], v[32:35]
	v_mfma_f32_16x16x32_bf16 v[28:31], v[158:161], v[174:177], v[28:31]
	v_mfma_f32_16x16x32_bf16 v[16:19], v[150:153], v[200:203], v[16:19]
	v_mfma_f32_16x16x32_bf16 v[12:15], v[158:161], v[200:203], v[12:15]
	v_mfma_f32_16x16x32_bf16 v[4:7], v[150:153], v[208:211], v[4:7]
	v_mfma_f32_16x16x32_bf16 v[0:3], v[158:161], v[208:211], v[0:3]
	s_setprio 0
	s_barrier
	s_add_u32 s12, s12, 0x100
	s_addc_u32 s13, s13, 0
	s_add_u32 s0, s0, 0x100
	s_addc_u32 s1, s1, 0
	s_cmp_ge_i32 s6, s10
	s_mov_b32 s4, s6
	s_cbranch_scc0 .LBB0_1376
	s_and_b64 vcc, exec, s[50:51]
	s_cbranch_vccz .LBB0_1379
	s_barrier
